# speedup vs baseline: 1.0486x; 1.0111x over previous
; __device__ __forceinline__ int opaque_tid(int wave_s) { int l; asm volatile("v_mbcnt_lo_u32_b32 %0, -1, 0\n\tv_mbcnt_hi_u32_b32 %0, -1, %0" : "=v"(l)); return (wave_s << 6) | l; }
; __device__ __forceinline__ void norm_row(const float* src, const float* g, bf16* dst, float* hdst, int lane) {
;     f32x4 v[8]; float ss = 0.f;
; #pragma unroll
;     for (int j = 0; j < 8; ++j) { v[j] = src ? *(const f32x4*)(src + 4 * lane + 256 * j) : (f32x4){0.f, 0.f, 0.f, 0.f}; ss += v[j].x * v[j].x + v[j].y * v[j].y + v[j].z * v[j].z + v[j].w * v[j].w; }
;     ss = wave_sum(ss);
;     const float rstd = rsqrtf(ss * (1.0f / DM) + EPS);
; __device__ __forceinline__ void phase_norm(KA a, const float* g, int vcu, int G, int wave) {
;     const int lane = opaque_tid(wave) & 63;
;     const int gw = vcu * NWAVES + wave, NGW = G * NWAVES;
;     for (int t = gw; t < T_; t += NGW) norm_row((const float*)(a->ws + WS_H) + (size_t)t * DM, g, (bf16*)(a->ws + WS_HN) + (size_t)t * DM, nullptr, lane);
; }
.LBB0_97:
	s_lshl_b32 s5, s81, 8
	s_add_i32 s5, s5, s11
	s_sub_i32 s5, s5, s81
	s_add_i32 s40, s5, s81
	s_cmpk_lt_i32 s40, 0x2010
	v_mbcnt_lo_u32_b32 v0, -1, 0
	v_mbcnt_hi_u32_b32 v0, -1, v0
	s_cbranch_scc0 .LBB0_100
	v_and_b32_e32 v1, 64, v196
	v_add_u32_e32 v1, 64, v1
	v_xor_b32_e32 v2, 1, v196
	v_cmp_lt_i32_e32 vcc, v2, v1
	s_load_dwordx2 s[18:19], s[36:37], 0xb8
	v_readlane_b32 s1, v254, 62
	v_cndmask_b32_e32 v2, v196, v2, vcc
	v_lshlrev_b32_e32 v48, 2, v2
	v_xor_b32_e32 v2, 2, v196
	v_cmp_lt_i32_e32 vcc, v2, v1
	s_lshl_b32 s20, s1, 11
	s_ashr_i32 s21, s20, 31
	v_cndmask_b32_e32 v2, v196, v2, vcc
	v_lshlrev_b32_e32 v49, 2, v2
	v_xor_b32_e32 v2, 4, v196
	v_cmp_lt_i32_e32 vcc, v2, v1
	s_lshl_b32 s42, s15, 3
	s_lshl_b64 s[20:21], s[20:21], 2
	v_cndmask_b32_e32 v2, v196, v2, vcc
	v_lshlrev_b32_e32 v50, 2, v2
	v_xor_b32_e32 v2, 8, v196
	v_cmp_lt_i32_e32 vcc, v2, v1
	s_waitcnt lgkmcnt(0)
	s_add_u32 s18, s18, s20
	s_addc_u32 s19, s19, s21
	v_cndmask_b32_e32 v2, v196, v2, vcc
	v_lshlrev_b32_e32 v51, 2, v2
	v_xor_b32_e32 v2, 16, v196
	v_cmp_lt_i32_e32 vcc, v2, v1
	s_ashr_i32 s41, s40, 31
	s_ashr_i32 s43, s42, 31
	v_cndmask_b32_e32 v2, v196, v2, vcc
	v_lshlrev_b32_e32 v52, 2, v2
	v_xor_b32_e32 v2, 32, v196
	v_cmp_lt_i32_e32 vcc, v2, v1
	s_lshl_b64 s[44:45], s[42:43], 12
	s_lshl_b64 s[48:49], s[42:43], 13
	v_cndmask_b32_e32 v1, v196, v2, vcc
	v_lshlrev_b32_e32 v53, 2, v1
	v_lshlrev_b32_e32 v1, 4, v0
	v_and_b32_e32 v148, 0x3f0, v1
	v_lshl_add_u64 v[32:33], s[18:19], 0, v[148:149]
	s_mov_b64 s[18:19], 0x1000
	v_lshl_add_u64 v[34:35], v[32:33], 0, s[18:19]
	s_mov_b64 s[18:19], 0x1400
	v_lshl_add_u64 v[36:37], v[32:33], 0, s[18:19]
	s_mov_b64 s[18:19], 0x1800
	v_lshl_add_u64 v[38:39], v[32:33], 0, s[18:19]
	s_mov_b64 s[18:19], 0x1c00
	v_lshl_add_u64 v[40:41], v[32:33], 0, s[18:19]
	s_lshl_b64 s[18:19], s[40:41], 12
	v_and_b32_e32 v0, 63, v0
	v_lshl_or_b32 v42, v0, 3, s18
	v_mov_b32_e32 v43, s19
	s_lshl_b64 s[18:19], s[40:41], 13
	v_lshl_or_b32 v44, v0, 4, s18
	v_mov_b32_e32 v45, s19

; __device__ __forceinline__ int opaque_tid(int wave_s) { int l; asm volatile("v_mbcnt_lo_u32_b32 %0, -1, 0\n\tv_mbcnt_hi_u32_b32 %0, -1, %0" : "=v"(l)); return (wave_s << 6) | l; }
; #define LAS __attribute__((address_space(3)))
; __device__ __forceinline__ void phase_mix(KA a, int l, LAS unsigned char* lds, int vcu, int G, int wave) {
;     const int lane = opaque_tid(wave) & 63;
;     const int gw = vcu * NWAVES + wave, NGW = G * NWAVES, tid = wave * 64 + lane;
;     const float* ga = a->in[I_AOG] + l * 1024; const float* gy = a->in[I_HOG] + l * 1024;
;     bf16* MIX = (bf16*)(a->ws + WS_MIX);
;     for (int t = gw; t < T_; t += NGW) {
;         const bf16* row = (const bf16*)(a->ws + WS_AO) + (size_t)t * 1024;
;         float v[16]; float ss = 0.f;
;         if (t < 8192) {
;             u32x4 x[2]; x[0] = *(const u32x4*)(row + lane * 8); x[1] = *(const u32x4*)(row + 512 + lane * 8);
.LBB0_130:
	s_and_b64 vcc, exec, s[22:23]
	s_cbranch_vccz .LBB0_159
	v_readlane_b32 s0, v254, 62
	s_lshl_b32 s5, s81, 8
	s_add_i32 s5, s5, s11
	s_sub_i32 s5, s5, s81
	s_lshl_b32 s42, s0, 10
	v_mbcnt_lo_u32_b32 v26, -1, 0
	v_mbcnt_hi_u32_b32 v26, -1, v26
	s_load_dwordx2 s[48:49], s[36:37], 0xa8
	s_add_i32 s44, s5, s81
	s_ashr_i32 s43, s42, 31
	s_add_u32 s40, s16, 0x20c90000
	s_addc_u32 s41, s17, 0
	v_and_b32_e32 v27, 63, v26
	s_cmpk_lt_i32 s44, 0x2010
	v_lshlrev_b32_e32 v148, 5, v27
	s_waitcnt vmcnt(0)
	v_lshlrev_b32_e32 v8, 4, v27
	s_cbranch_scc0 .LBB0_142
	s_load_dwordx2 s[18:19], s[36:37], 0xa0
	s_lshl_b32 s7, s15, 3
	s_add_u32 s52, s16, 0x2f3a0000
	s_addc_u32 s53, s17, 0
	s_lshl_b64 s[20:21], s[42:43], 2
	s_waitcnt lgkmcnt(0)
	s_add_u32 s18, s18, s20
	s_addc_u32 s19, s19, s21
	v_lshrrev_b32_e32 v2, 4, v27
	v_mov_b32_e32 v9, v149
	v_mov_b32_e32 v0, 0x840
	s_movk_i32 s1, 0x210
	v_lshl_add_u64 v[10:11], s[18:19], 0, v[148:149]
	v_mad_u32_u24 v29, v2, s1, v0
	v_lshl_add_u64 v[0:1], s[16:17], 0, v[8:9]
	s_mov_b64 s[18:19], 0x1eb90000
	v_lshl_add_u64 v[14:15], v[0:1], 0, s[18:19]
	v_and_b32_e32 v0, 15, v26
	v_readlane_b32 s0, v254, 43
	v_lshlrev_b32_e32 v0, 5, v0
	v_mov_b32_e32 v1, v149
	s_add_i32 s3, s5, s0
	v_readlane_b32 s0, v254, 44
	v_lshl_add_u64 v[16:17], s[16:17], 0, v[0:1]
	v_mov_b32_e32 v0, s3
	s_add_i32 s3, s5, s0
	v_lshl_add_u64 v[12:13], s[40:41], 0, v[8:9]
	v_mad_u32_u24 v9, v2, s1, v0
	v_mov_b32_e32 v0, s3
	v_mul_u32_u24_e32 v28, 0x210, v2
	v_mad_u32_u24 v30, v2, s1, v0
	global_load_dwordx2 v[232:233], v[10:11], off
	global_load_dwordx2 v[234:235], v[10:11], off offset:8
	global_load_dwordx2 v[236:237], v[10:11], off offset:16
	global_load_dwordx2 v[238:239], v[10:11], off offset:24
	global_load_dwordx2 v[240:241], v[10:11], off offset:2048
	global_load_dwordx2 v[242:243], v[10:11], off offset:2056
	global_load_dwordx2 v[244:245], v[10:11], off offset:2064
	global_load_dwordx2 v[246:247], v[10:11], off offset:2072
	s_branch .LBB0_134

; __device__ __forceinline__ int opaque_tid(int wave_s) { int l; asm volatile("v_mbcnt_lo_u32_b32 %0, -1, 0\n\tv_mbcnt_hi_u32_b32 %0, -1, %0" : "=v"(l)); return (wave_s << 6) | l; }
; __device__ __forceinline__ u32x4_h zero4u() { unsigned z = 0u; asm volatile("" : "+v"(z)); return (u32x4_h){z, z, z, z}; }
; __device__ __forceinline__ void phase_prep(KA a, int l, int vcu, int G, int wave) {
;     const int lane = opaque_tid(wave) & 63;
;     const int gw = vcu * NWAVES + wave, NGW = G * NWAVES;
;     const float* gq = a->in[I_QNG] + l * QKD; const float* gk = a->in[I_KNG] + l * QKD;
;     for (int i = gw * 64 + lane; i < 48 * NH * QKD / 8; i += NGW * 64) {
;         const int r = i / (QKD / 8), cch = i % (QKD / 8), h = r / 48, tt = T_ + r % 48;
;         *(u32x4*)((bf16*)(a->ws + WS_K) + ((size_t)h * TP + tt) * QKD + cch * 8) = zero4u(); }
;     for (int i = gw * 64 + lane; i < 48 * 256; i += NGW * 64) *(u32x4*)((bf16*)(a->ws + WS_KVRAW) + (size_t)(T_ + i / 256) * 2048 + (i % 256) * 8) = zero4u();
.LBB0_366:
	s_and_b64 vcc, exec, s[22:23]
	s_cbranch_vccz .LBB0_376
	v_mbcnt_lo_u32_b32 v48, -1, 0
	v_mbcnt_hi_u32_b32 v48, -1, v48
	s_load_dwordx4 s[40:43], s[36:37], 0x40
	s_lshl_b32 s5, s81, 8
	s_add_i32 s5, s5, s11
	s_sub_i32 s5, s5, s81
	s_add_i32 s44, s5, s81
	v_and_b32_e32 v49, 63, v48
	v_lshl_or_b32 v1, s44, 6, v49
	s_movk_i32 s7, 0x2400
	s_lshl_b32 s5, s15, 9
	v_cmp_gt_i32_e32 vcc, s7, v1
	v_lshlrev_b32_e32 v2, 3, v1
	s_and_saveexec_b64 s[46:47], vcc
	s_mov_b32 s0, 0x2aaaaaab
	s_cbranch_execz .LBB0_370
	s_add_u32 s48, s16, 0x298d0000
	s_addc_u32 s49, s17, 0
	v_lshlrev_b32_e32 v0, 3, v1
	s_lshl_b32 s7, s5, 3
	s_mov_b64 s[52:53], 0
	v_mov_b32_e32 v3, v1
	s_waitcnt vmcnt(0)

; __device__ __forceinline__ unsigned pk2(float lo, float hi) { return pg8::cvt_pk_bf16(lo, hi); }
; __device__ __forceinline__ float bflo(unsigned w) { return __uint_as_float(w << 16); }
; __device__ __forceinline__ float bfhi(unsigned w) { return __uint_as_float(w & 0xffff0000u); }
; __device__ __forceinline__ void phase_prep(KA a, int l, int vcu, int G, int wave) {
;     ...
;     const int hh = lane >> 3, j = lane & 7;
;     float gqv[24], gkv[24];
; #pragma unroll
;     for (int c = 0; c < 3; ++c)
; #pragma unroll
;         for (int e = 0; e < 8; ++e) { gqv[c * 8 + e] = gq[c * 64 + 8 * j + e]; gkv[c * 8 + e] = gk[c * 64 + 8 * j + e]; }
;     auto unpack8 = [](const u32x4 w, float* o) { o[0] = bflo(w.x); o[1] = bfhi(w.x); o[2] = bflo(w.y); o[3] = bfhi(w.y); o[4] = bflo(w.z); o[5] = bfhi(w.z); o[6] = bflo(w.w); o[7] = bfhi(w.w); };
;     auto pack8 = [](const float* v) { u32x4 w; w.x = pk2(v[0], v[1]); w.y = pk2(v[2], v[3]); w.z = pk2(v[4], v[5]); w.w = pk2(v[6], v[7]); return w; };
; #pragma unroll 1
;     for (int t = gw; t < T_; t += NGW) {
;         const bf16* qrow = (const bf16*)(a->ws + WS_QRAW) + (size_t)t * 1536 + hh * QKD + 8 * j;
;         const bf16* kvrow = (const bf16*)(a->ws + WS_KVRAW) + (size_t)t * 2048 + hh * 256 + 8 * j;
;         const bf16* krow = (const bf16*)(a->ws + WS_ATT) + (size_t)t * 1024 + 768 + 8 * j;
;         const f32x4* cst = (const f32x4*)((const f32x2*)(a->ws + WS_ROPE) + t * 32 + 8 * (j & 3));
;         const u32x4 q0 = *(const u32x4*)qrow, q1 = *(const u32x4*)(qrow + 64), q2 = *(const u32x4*)(qrow + 128);
;         const u32x4 k0 = *(const u32x4*)kvrow, k1 = *(const u32x4*)(kvrow + 64), k2 = *(const u32x4*)krow;
;         const f32x4 cs0 = cst[0], cs1 = cst[1], cs2 = cst[2], cs3 = cst[3];
;         const float cc[8] = {cs0.x, cs0.z, cs1.x, cs1.z, cs2.x, cs2.z, cs3.x, cs3.z}, sn[8] = {cs0.y, cs0.w, cs1.y, cs1.w, cs2.y, cs2.w, cs3.y, cs3.w};
.LBB0_373:
	s_or_b64 exec, exec, s[22:23]
	s_cmpk_lt_i32 s44, 0x2010
	s_mov_b32 s9, 0x800000
	s_cbranch_scc0 .LBB0_376
	v_readlane_b32 s0, v254, 62
	s_mul_i32 s18, s0, 0xc0
	s_ashr_i32 s19, s18, 31
	s_lshl_b64 s[18:19], s[18:19], 2
	s_waitcnt lgkmcnt(0)
	s_add_u32 s20, s40, s18
	s_addc_u32 s21, s41, s19
	v_and_b32_e32 v50, 7, v48
	s_add_u32 s18, s42, s18
	v_lshlrev_b32_e32 v44, 5, v50
	s_addc_u32 s19, s43, s19
	global_load_dwordx4 v[0:3], v44, s[20:21]
	global_load_dwordx4 v[4:7], v44, s[20:21] offset:16
	global_load_dwordx4 v[8:11], v44, s[18:19]
	global_load_dwordx4 v[12:15], v44, s[18:19] offset:16
	global_load_dwordx4 v[16:19], v44, s[20:21] offset:256
	global_load_dwordx4 v[20:23], v44, s[20:21] offset:272
	global_load_dwordx4 v[24:27], v44, s[18:19] offset:256
	global_load_dwordx4 v[28:31], v44, s[18:19] offset:272
	global_load_dwordx4 v[32:35], v44, s[18:19] offset:512
	global_load_dwordx4 v[36:39], v44, s[18:19] offset:528
	global_load_dwordx4 v[40:43], v44, s[20:21] offset:512
	s_nop 0
	global_load_dwordx4 v[44:47], v44, s[20:21] offset:528
	v_lshlrev_b32_e32 v53, 6, v48
	v_and_b32_e32 v148, 0xc0, v53
	v_lshrrev_b32_e32 v51, 3, v49
	v_lshl_add_u64 v[48:49], s[16:17], 0, v[148:149]
	s_mov_b64 s[0:1], 0x1e980000
	v_lshl_add_u64 v[76:77], v[48:49], 0, s[0:1]
	v_and_b32_e32 v49, 64, v196
	v_xor_b32_e32 v48, 1, v196
	v_add_u32_e32 v49, 64, v49
	v_cmp_lt_i32_e32 vcc, v48, v49
	s_lshl_b32 s3, s11, 8
	v_readlane_b32 s0, v253, 16
	v_cndmask_b32_e32 v48, v196, v48, vcc
	v_lshlrev_b32_e32 v86, 2, v48
	v_xor_b32_e32 v48, 2, v196
	v_cmp_lt_i32_e32 vcc, v48, v49
	s_lshl_b32 s42, s15, 3
	s_lshl_b32 s46, s44, 5
	v_cndmask_b32_e32 v48, v196, v48, vcc
	v_lshlrev_b32_e32 v87, 2, v48
	v_xor_b32_e32 v48, 4, v196
	v_cmp_lt_i32_e32 vcc, v48, v49
	s_lshl_b32 s7, s15, 8
	s_ashr_i32 s45, s44, 31
	s_mul_i32 s5, s44, 0xc00
	v_mul_u32_u24_e32 v52, 0xc0, v51
	v_cndmask_b32_e32 v48, v196, v48, vcc
	s_mul_hi_i32 s3, s44, 0xc00
	s_add_u32 s18, s16, s5
	v_lshlrev_b32_e32 v88, 2, v48
	v_cmp_gt_u32_e64 s[40:41], 4, v50
	v_mul_u32_u24_e32 v48, 0x2100, v51
	v_lshlrev_b32_e32 v148, 4, v50
	v_lshlrev_b32_e32 v50, 1, v52
	v_mov_b32_e32 v51, v149
	s_addc_u32 s19, s17, s3
	v_lshl_add_u64 v[50:51], s[18:19], 0, v[50:51]
	s_mov_b64 s[18:19], 0x20870080
	v_lshl_add_u64 v[78:79], v[50:51], 0, s[18:19]
	s_ashr_i32 s43, s42, 31
	s_lshl_b64 s[18:19], s[44:45], 12
	s_add_u32 s18, s16, s18
	v_mov_b32_e32 v49, v149
	v_and_b32_e32 v50, 0xe00, v53
	v_mov_b32_e32 v51, v149
	s_addc_u32 s19, s17, s19
	v_lshl_add_u64 v[80:81], s[18:19], 0, v[50:51]
	v_lshl_add_u64 v[48:49], s[44:45], 0, v[48:49]
	v_mov_b64_e32 v[50:51], s[16:17]
	v_mad_u64_u32 v[82:83], s[18:19], v48, s26, v[50:51]
	s_lshl_b64 s[52:53], s[42:43], 12
	s_lshl_b64 s[18:19], s[44:45], 11
	s_add_u32 s3, s16, s18
	s_addc_u32 s5, s17, s19
	s_add_u32 s56, s3, 0x1eb90600
	s_mul_i32 s48, s15, 0x6000
	s_mul_hi_i32 s49, s42, 0xc00
	v_mad_i32_i24 v83, v49, s26, v83
	s_mul_i32 s54, s15, 0xc00
	s_mul_hi_i32 s55, s42, 0x180
	s_addc_u32 s57, s5, 0
	s_lshl_b64 s[58:59], s[42:43], 11
	v_readlane_b32 s1, v253, 17

; __device__ __forceinline__ int opaque_tid(int wave_s) { int l; asm volatile("v_mbcnt_lo_u32_b32 %0, -1, 0\n\tv_mbcnt_hi_u32_b32 %0, -1, %0" : "=v"(l)); return (wave_s << 6) | l; }
; __device__ __forceinline__ float bflo(unsigned w) { return __uint_as_float(w << 16); }
; __device__ __forceinline__ float bfhi(unsigned w) { return __uint_as_float(w & 0xffff0000u); }
; __device__ __forceinline__ void phase_lat(KA a, int l, int vcu, int G, int wave) {
;     const int lane = opaque_tid(wave) & 63;
;     const int gw = vcu * NWAVES + wave, NGW = G * NWAVES;
;     const float* gq = a->in[I_QLG] + l * QL; const float* gk = a->in[I_KVLG] + l * KVL;
;     for (int t = gw; t < T_; t += NGW) {
;         const bf16* row = (const bf16*)(a->ws + WS_ATT) + (size_t)t * 1024;
;         const u32x4 q = *(const u32x4*)(row + lane * 8); const u32x2 k = *(const u32x2*)(row + 512 + lane * 4);
;         float qv[8] = {bflo(q.x), bfhi(q.x), bflo(q.y), bfhi(q.y), bflo(q.z), bfhi(q.z), bflo(q.w), bfhi(q.w)};
;         float kv[4] = {bflo(k.x), bfhi(k.x), bflo(k.y), bfhi(k.y)};
;         float sq = 0.f, sk = 0.f;
; #pragma unroll
;         for (int e = 0; e < 8; ++e) sq += qv[e] * qv[e];
; #pragma unroll
;         for (int e = 0; e < 4; ++e) sk += kv[e] * kv[e];
;         sq = wave_sum(sq); sk = wave_sum(sk);
;         const float rq = rsqrtf(sq * (1.0f / QL) + EPS), rk = rsqrtf(sk * (1.0f / KVL) + EPS);
;         const f32x4 g0 = *(const f32x4*)(gq + lane * 8), g1 = *(const f32x4*)(gq + lane * 8 + 4), g2 = *(const f32x4*)(gk + lane * 4);
.LBB0_425:
	s_andn2_b64 vcc, exec, s[22:23]
	s_mov_b64 s[46:47], 0
	s_cbranch_vccnz .LBB0_433
	s_cmp_gt_i32 s66, 0
	s_mov_b64 s[22:23], -1
	s_cbranch_scc0 .LBB0_431
	s_lshl_b32 s5, s81, 8
	s_add_i32 s5, s5, s11
	s_sub_i32 s5, s5, s81
	s_waitcnt lgkmcnt(0)
	s_add_i32 s42, s5, s81
	s_mov_b32 s0, 0x3b800000
	s_cmpk_lt_i32 s42, 0x2010
	s_mov_b32 s1, 0x3b000000
	s_mov_b32 s3, 0x800000
	v_mbcnt_lo_u32_b32 v0, -1, 0
	v_mbcnt_hi_u32_b32 v0, -1, v0
	s_cbranch_scc0 .LBB0_430
	v_and_b32_e32 v2, 63, v0
	v_and_b32_e32 v0, 64, v196
	v_add_u32_e32 v0, 64, v0
	v_xor_b32_e32 v1, 1, v196
	v_cmp_lt_i32_e32 vcc, v1, v0
	s_load_dwordx4 s[20:23], s[36:37], 0x20
	v_readlane_b32 s5, v254, 62
	v_cndmask_b32_e32 v1, v196, v1, vcc
	v_lshlrev_b32_e32 v26, 2, v1
	v_xor_b32_e32 v1, 2, v196
	v_cmp_lt_i32_e32 vcc, v1, v0
	s_lshl_b32 s24, s5, 8
	s_lshl_b32 s18, s5, 9
	v_cndmask_b32_e32 v1, v196, v1, vcc
	v_lshlrev_b32_e32 v27, 2, v1
	v_xor_b32_e32 v1, 4, v196
	v_cmp_lt_i32_e32 vcc, v1, v0
	s_ashr_i32 s25, s24, 31
	s_lshl_b32 s44, s15, 3
	v_cndmask_b32_e32 v1, v196, v1, vcc
	v_lshlrev_b32_e32 v28, 2, v1
	v_xor_b32_e32 v1, 8, v196
	v_cmp_lt_i32_e32 vcc, v1, v0
	s_ashr_i32 s19, s18, 31
	s_lshl_b64 s[24:25], s[24:25], 2
	v_cndmask_b32_e32 v1, v196, v1, vcc
	v_lshlrev_b32_e32 v29, 2, v1
	v_xor_b32_e32 v1, 16, v196
	v_cmp_lt_i32_e32 vcc, v1, v0
	s_waitcnt lgkmcnt(0)
	s_add_u32 s22, s22, s24
	s_addc_u32 s23, s23, s25
	v_cndmask_b32_e32 v1, v196, v1, vcc
	v_lshlrev_b32_e32 v30, 2, v1
	v_xor_b32_e32 v1, 32, v196
	s_lshl_b64 s[18:19], s[18:19], 2
	v_cmp_lt_i32_e32 vcc, v1, v0
	s_add_u32 s18, s20, s18
	s_addc_u32 s19, s21, s19
	v_cndmask_b32_e32 v0, v196, v1, vcc
	v_lshlrev_b32_e32 v31, 2, v0
	v_lshlrev_b32_e32 v0, 5, v2
	v_mov_b32_e32 v1, v149
	s_ashr_i32 s43, s42, 31
	v_lshl_add_u64 v[0:1], s[18:19], 0, v[0:1]
	s_lshl_b64 s[18:19], s[42:43], 9
	s_add_u32 s18, s16, s18
	v_lshlrev_b32_e32 v148, 3, v2
	s_addc_u32 s19, s17, s19
	v_lshl_add_u64 v[4:5], s[18:19], 0, v[148:149]
	s_mov_b64 s[18:19], 0x20450000
	s_ashr_i32 s45, s44, 31
	v_lshl_add_u64 v[4:5], v[4:5], 0, s[18:19]
	s_lshl_b64 s[46:47], s[44:45], 9
	s_lshl_b64 s[18:19], s[42:43], 10
	s_add_u32 s18, s16, s18
	v_lshlrev_b32_e32 v10, 4, v2
	v_mov_b32_e32 v11, v149
	s_addc_u32 s19, s17, s19
	v_lshl_add_u64 v[6:7], s[18:19], 0, v[10:11]
	s_mov_b64 s[18:19], 0x1fc10000
	v_lshl_add_u64 v[6:7], v[6:7], 0, s[18:19]
	s_lshl_b64 s[48:49], s[44:45], 10
	s_lshl_b64 s[18:19], s[42:43], 11
	s_add_u32 s5, s18, 0x1eb90400
	s_addc_u32 s7, s19, 0
	s_lshl_b64 s[52:53], s[44:45], 11
	s_waitcnt vmcnt(0)
	v_or_b32_e32 v8, s5, v148
	s_add_u32 s5, s18, 0x1eb90000
	v_mov_b32_e32 v9, s7
	s_addc_u32 s7, s19, 0
	v_lshl_add_u64 v[2:3], s[22:23], 0, v[10:11]
	v_or_b32_e32 v10, s5, v10
	v_mov_b32_e32 v11, s7
	s_mov_b64 s[54:55], s[16:17]

; __device__ __forceinline__ int opaque_tid(int wave_s) { int l; asm volatile("v_mbcnt_lo_u32_b32 %0, -1, 0\n\tv_mbcnt_hi_u32_b32 %0, -1, %0" : "=v"(l)); return (wave_s << 6) | l; }
; __device__ __forceinline__ void norm_row(const float* src, const float* g, bf16* dst, float* hdst, int lane) {
;     f32x4 v[8]; float ss = 0.f;
; #pragma unroll
;     for (int j = 0; j < 8; ++j) { v[j] = src ? *(const f32x4*)(src + 4 * lane + 256 * j) : (f32x4){0.f, 0.f, 0.f, 0.f}; ss += v[j].x * v[j].x + v[j].y * v[j].y + v[j].z * v[j].z + v[j].w * v[j].w; }
;     ss = wave_sum(ss);
;     const float rstd = rsqrtf(ss * (1.0f / DM) + EPS);
; #pragma unroll
;     for (int j = 0; j < 8; ++j) {
;         const f32x4 gg = *(const f32x4*)(g + 4 * lane + 256 * j);
; __device__ __forceinline__ void phase_norm(KA a, const float* g, int vcu, int G, int wave) {
;     const int lane = opaque_tid(wave) & 63;
;     const int gw = vcu * NWAVES + wave, NGW = G * NWAVES;
;     for (int t = gw; t < T_; t += NGW) norm_row((const float*)(a->ws + WS_H) + (size_t)t * DM, g, (bf16*)(a->ws + WS_HN) + (size_t)t * DM, nullptr, lane);
; }
.LBB0_434:
	s_and_b64 vcc, exec, s[0:1]
	s_cbranch_vccz .LBB0_439
	s_lshl_b32 s5, s81, 8
	s_add_i32 s5, s5, s11
	s_sub_i32 s5, s5, s81
	s_add_i32 s20, s5, s81
	s_cmpk_lt_i32 s20, 0x2010
	s_mov_b32 s0, 0x1b800000
	v_mbcnt_lo_u32_b32 v0, -1, 0
	v_mbcnt_hi_u32_b32 v0, -1, v0
	s_cbranch_scc0 .LBB0_438
	v_and_b32_e32 v1, 64, v196
	v_add_u32_e32 v1, 64, v1
	v_xor_b32_e32 v2, 1, v196
	v_cmp_lt_i32_e32 vcc, v2, v1
	s_load_dwordx2 s[18:19], s[36:37], 0x10
	v_readlane_b32 s1, v254, 62
	v_cndmask_b32_e32 v2, v196, v2, vcc
	v_lshlrev_b32_e32 v48, 2, v2
	v_xor_b32_e32 v2, 2, v196
	v_cmp_lt_i32_e32 vcc, v2, v1
	s_lshl_b32 s3, s1, 11
	s_add_i32 s22, s3, 0x800
	v_cndmask_b32_e32 v2, v196, v2, vcc
	v_lshlrev_b32_e32 v49, 2, v2
	v_xor_b32_e32 v2, 4, v196
	v_cmp_lt_i32_e32 vcc, v2, v1
	s_ashr_i32 s23, s22, 31
	s_waitcnt lgkmcnt(0)
	s_lshl_b32 s40, s15, 3
	v_cndmask_b32_e32 v2, v196, v2, vcc
	v_lshlrev_b32_e32 v50, 2, v2
	v_xor_b32_e32 v2, 8, v196
	v_cmp_lt_i32_e32 vcc, v2, v1
	s_lshl_b64 s[22:23], s[22:23], 2
	s_add_u32 s18, s18, s22
	v_cndmask_b32_e32 v2, v196, v2, vcc
	v_lshlrev_b32_e32 v51, 2, v2
	v_xor_b32_e32 v2, 16, v196
	v_cmp_lt_i32_e32 vcc, v2, v1
	s_addc_u32 s19, s19, s23
	s_ashr_i32 s21, s20, 31
	v_cndmask_b32_e32 v2, v196, v2, vcc
	v_lshlrev_b32_e32 v52, 2, v2
	v_xor_b32_e32 v2, 32, v196
	v_cmp_lt_i32_e32 vcc, v2, v1
	s_ashr_i32 s41, s40, 31
	s_lshl_b64 s[42:43], s[40:41], 12
	v_cndmask_b32_e32 v1, v196, v2, vcc
	v_lshlrev_b32_e32 v53, 2, v1
	v_lshlrev_b32_e32 v1, 4, v0
	v_and_b32_e32 v148, 0x3f0, v1
	v_lshl_add_u64 v[32:33], s[18:19], 0, v[148:149]
	s_mov_b64 s[18:19], 0x1000
	v_lshl_add_u64 v[34:35], v[32:33], 0, s[18:19]
	s_mov_b64 s[18:19], 0x1400
	v_lshl_add_u64 v[36:37], v[32:33], 0, s[18:19]
	s_mov_b64 s[18:19], 0x1800
	v_lshl_add_u64 v[38:39], v[32:33], 0, s[18:19]
	s_mov_b64 s[18:19], 0x1c00
	v_lshl_add_u64 v[40:41], v[32:33], 0, s[18:19]
	s_lshl_b64 s[18:19], s[20:21], 12
	v_and_b32_e32 v0, 63, v0
	v_lshl_or_b32 v42, v0, 3, s18
	v_mov_b32_e32 v43, s19
	s_lshl_b64 s[18:19], s[20:21], 13
	v_lshl_or_b32 v44, v0, 4, s18
	v_mov_b32_e32 v45, s19
	s_lshl_b64 s[44:45], s[40:41], 13
